# v34: v22 without s_setprio around the GEMM K-loop MFMA sections (second sitting)
# speedup vs baseline: 1.0247x; 1.0066x over previous
; #define G_STAGE(bufoff, gbase, voff) do { _Pragma("unroll") for (int _i = 0; _i < 2; ++_i) \
;     __builtin_amdgcn_global_load_lds((const unsigned*)((const char*)(gbase) + (voff)[_i]), (LAS unsigned*)(lds + (bufoff) + ldsw + _i * 8192), 16, 0, 0); } while (0)
; #define G_LDA(dst, b, h) do { _Pragma("unroll") for (int m = 0; m < 4; ++m) _Pragma("unroll") for (int k = 0; k < 2; ++k) dst[m][k] = *(const LAS bf16x8*)(lds + G_SA(b, h) + aoff + m * 2048 + k * 1024); } while (0)
; #define G_LDB(dst, b, h) do { _Pragma("unroll") for (int n = 0; n < 2; ++n) _Pragma("unroll") for (int k = 0; k < 2; ++k) dst[n][k] = *(const LAS bf16x8*)(lds + G_SB(b, h) + boff + n * 2048 + k * 1024); } while (0)
; #define G_MMA(ai, bj, At, Bt) do { __builtin_amdgcn_s_setprio(1); _Pragma("unroll") for (int m = 0; m < 4; ++m) _Pragma("unroll") for (int n = 0; n < 2; ++n) _Pragma("unroll") for (int k = 0; k < 2; ++k) \
;     acc[ai][bj][m][n] = __builtin_amdgcn_mfma_f32_16x16x32_bf16(Bt[n][k], At[m][k], acc[ai][bj][m][n], 0, 0, 0); __builtin_amdgcn_s_setprio(0); } while (0)
; #define G_WAIT_V(n) asm volatile("s_waitcnt vmcnt(" #n ")" ::: "memory")
; #define G_WAIT_L(n) asm volatile("s_waitcnt lgkmcnt(" #n ")" ::: "memory")
; #define G_BAR __builtin_amdgcn_s_barrier()
; #define G_SCHED __builtin_amdgcn_sched_barrier(0)
; template <int GP> DI void gemm_phase(const Params& p, int l, int which, char* smem, int wv) {
;     ...
;       G_LDB(B0, 0, 0); G_SCHED; G_LDA(At, 0, 0); G_STAGE(G_SA(1, 1), a1 + hstep, voffA);
;       G_WAIT_L(8); G_BAR; G_WAIT_L(0); G_MMA(0, 0, At, B0); G_BAR; G_SCHED;
;       G_LDB(B1, 0, 1); G_STAGE(G_SB(0, 0), b2, vb0);
;       G_BAR; G_WAIT_L(0); G_MMA(0, 1, At, B1); G_BAR;
;       G_LDA(At, 0, 1); G_STAGE(G_SA(0, 0), a2, voffA);
;       G_BAR; G_WAIT_L(0); G_MMA(1, 0, At, B0); G_BAR; G_SCHED;
;       G_STAGE(G_SB(0, 1), b2, vb1);
;       G_WAIT_V(6); G_BAR; G_MMA(1, 1, At, B1); G_BAR;
;       G_LDB(B0, 1, 0); G_SCHED; G_LDA(At, 1, 0); G_STAGE(G_SA(0, 1), a2 + hstep, voffA);
;       G_WAIT_L(8); G_BAR; G_WAIT_L(0); G_MMA(0, 0, At, B0); G_BAR; G_SCHED;
;       G_LDB(B1, 1, 1); G_STAGE(G_SB(1, 0), b3, vb0);
;       G_BAR; G_WAIT_L(0); G_MMA(0, 1, At, B1); G_BAR;
;       G_LDA(At, 1, 1); G_STAGE(G_SA(1, 0), a3, voffA);
;       G_BAR; G_WAIT_L(0); G_MMA(1, 0, At, B0); G_BAR; G_SCHED;
;       G_STAGE(G_SB(1, 1), b3, vb1);
;       G_WAIT_V(6); G_BAR; G_MMA(1, 1, At, B1); G_BAR;
.LBB0_149:
	v_add_u32_e32 v135, 0x10000, v166
	s_add_u32 s61, s8, s26
	ds_read_b128 v[168:171], v135
	ds_read_b128 v[172:175], v135 offset:1024
	ds_read_b128 v[176:179], v135 offset:2048
	ds_read_b128 v[180:183], v135 offset:3072
	s_addc_u32 s62, s9, s27
	s_and_b64 s[30:31], s[28:29], exec
	s_cselect_b32 s31, s11, s62
	s_cselect_b32 s30, s57, s61
	s_add_u32 s61, s6, s26
	s_addc_u32 s62, s7, s27
	s_and_b64 s[28:29], s[28:29], exec
	s_cselect_b32 s28, s59, s61
	s_cselect_b32 s29, s58, s62
	s_mov_b32 m0, s53
	v_lshl_add_u64 v[216:217], s[8:9], 0, v[162:163]
	ds_read_b128 v[184:187], v165
	ds_read_b128 v[188:191], v165 offset:1024
	ds_read_b128 v[192:195], v165 offset:2048
	ds_read_b128 v[196:199], v165 offset:3072
	ds_read_b128 v[200:203], v165 offset:4096
	ds_read_b128 v[204:207], v165 offset:5120
	ds_read_b128 v[208:211], v165 offset:6144
	ds_read_b128 v[212:215], v165 offset:7168
	global_load_lds_dwordx4 v[216:217], off
	v_lshl_add_u64 v[216:217], s[8:9], 0, v[160:161]
	s_mov_b32 m0, s54
	s_nop 0
	global_load_lds_dwordx4 v[216:217], off
	s_waitcnt lgkmcnt(8)
	s_barrier
	s_waitcnt lgkmcnt(0)
	s_waitcnt lgkmcnt(0)
	v_mfma_f32_16x16x32_bf16 v[62:65], v[168:171], v[184:187], v[62:65]
	v_mfma_f32_16x16x32_bf16 v[58:61], v[176:179], v[184:187], v[58:61]
	v_mfma_f32_16x16x32_bf16 v[54:57], v[168:171], v[192:195], v[54:57]
	v_mfma_f32_16x16x32_bf16 v[50:53], v[176:179], v[192:195], v[50:53]
	v_mfma_f32_16x16x32_bf16 v[46:49], v[168:171], v[200:203], v[46:49]
	v_mfma_f32_16x16x32_bf16 v[42:45], v[176:179], v[200:203], v[42:45]
	v_mfma_f32_16x16x32_bf16 v[38:41], v[168:171], v[208:211], v[38:41]
	v_mfma_f32_16x16x32_bf16 v[34:37], v[176:179], v[208:211], v[34:37]
	v_mfma_f32_16x16x32_bf16 v[62:65], v[172:175], v[188:191], v[62:65]
	v_mfma_f32_16x16x32_bf16 v[58:61], v[180:183], v[188:191], v[58:61]
	v_mfma_f32_16x16x32_bf16 v[54:57], v[172:175], v[196:199], v[54:57]
	v_mfma_f32_16x16x32_bf16 v[50:53], v[180:183], v[196:199], v[50:53]
	v_mfma_f32_16x16x32_bf16 v[46:49], v[172:175], v[204:207], v[46:49]
	v_mfma_f32_16x16x32_bf16 v[42:45], v[180:183], v[204:207], v[42:45]
	v_mfma_f32_16x16x32_bf16 v[38:41], v[172:175], v[212:215], v[38:41]
	v_mfma_f32_16x16x32_bf16 v[34:37], v[180:183], v[212:215], v[34:37]
	s_barrier
	s_mov_b32 m0, s1
	v_add_u32_e32 v135, 0x14000, v166
	ds_read_b128 v[216:219], v135
	ds_read_b128 v[220:223], v135 offset:1024
	ds_read_b128 v[224:227], v135 offset:2048
	ds_read_b128 v[238:241], v135 offset:3072
	global_load_lds_dwordx4 v0, s[28:29]
	s_mov_b32 m0, s3
	v_mov_b32_e32 v137, v1
	global_load_lds_dwordx4 v136, s[28:29]
	s_barrier
	s_waitcnt lgkmcnt(0)
	v_lshl_add_u64 v[228:229], s[28:29], 0, v[0:1]
	v_lshl_add_u64 v[234:235], s[28:29], 0, v[136:137]
	s_waitcnt lgkmcnt(0)
	v_mfma_f32_16x16x32_bf16 v[30:33], v[216:219], v[184:187], v[30:33]
	v_mfma_f32_16x16x32_bf16 v[26:29], v[224:227], v[184:187], v[26:29]
	v_mfma_f32_16x16x32_bf16 v[22:25], v[216:219], v[192:195], v[22:25]
	v_mfma_f32_16x16x32_bf16 v[18:21], v[224:227], v[192:195], v[18:21]
	v_mfma_f32_16x16x32_bf16 v[14:17], v[216:219], v[200:203], v[14:17]
	v_mfma_f32_16x16x32_bf16 v[10:13], v[224:227], v[200:203], v[10:13]
	v_mfma_f32_16x16x32_bf16 v[6:9], v[216:219], v[208:211], v[6:9]
	v_mfma_f32_16x16x32_bf16 v[2:5], v[224:227], v[208:211], v[2:5]
	v_mfma_f32_16x16x32_bf16 v[30:33], v[220:223], v[188:191], v[30:33]
	v_mfma_f32_16x16x32_bf16 v[26:29], v[238:241], v[188:191], v[26:29]
	v_mfma_f32_16x16x32_bf16 v[22:25], v[220:223], v[196:199], v[22:25]
	v_mfma_f32_16x16x32_bf16 v[18:21], v[238:241], v[196:199], v[18:21]
	v_mfma_f32_16x16x32_bf16 v[14:17], v[220:223], v[204:207], v[14:17]
	v_mfma_f32_16x16x32_bf16 v[10:13], v[238:241], v[204:207], v[10:13]
	v_mfma_f32_16x16x32_bf16 v[6:9], v[220:223], v[212:215], v[6:9]
	v_mfma_f32_16x16x32_bf16 v[2:5], v[238:241], v[212:215], v[2:5]
	s_mov_b32 m0, s38
	v_lshl_add_u64 v[242:243], s[30:31], 0, v[130:131]
	s_barrier
	ds_read_b128 v[184:187], v165 offset:16384
	ds_read_b128 v[188:191], v165 offset:17408
	ds_read_b128 v[192:195], v165 offset:18432
	ds_read_b128 v[196:199], v165 offset:19456
	ds_read_b128 v[200:203], v165 offset:20480
	ds_read_b128 v[204:207], v165 offset:21504
	ds_read_b128 v[208:211], v165 offset:22528
	ds_read_b128 v[212:215], v165 offset:23552
	global_load_lds_dwordx4 v[242:243], off
	v_lshl_add_u64 v[244:245], s[30:31], 0, v[132:133]
	s_mov_b32 m0, s5
	s_nop 0
	global_load_lds_dwordx4 v[244:245], off
	s_barrier
	s_waitcnt lgkmcnt(0)
	s_waitcnt lgkmcnt(0)
	v_mfma_f32_16x16x32_bf16 v[66:69], v[168:171], v[184:187], v[66:69]
	v_mfma_f32_16x16x32_bf16 v[70:73], v[176:179], v[184:187], v[70:73]
	v_mfma_f32_16x16x32_bf16 v[74:77], v[168:171], v[192:195], v[74:77]
	v_mfma_f32_16x16x32_bf16 v[78:81], v[176:179], v[192:195], v[78:81]
	v_mfma_f32_16x16x32_bf16 v[82:85], v[168:171], v[200:203], v[82:85]
	v_mfma_f32_16x16x32_bf16 v[86:89], v[176:179], v[200:203], v[86:89]
	v_mfma_f32_16x16x32_bf16 v[90:93], v[168:171], v[208:211], v[90:93]
	v_mfma_f32_16x16x32_bf16 v[98:101], v[176:179], v[208:211], v[98:101]
	v_mfma_f32_16x16x32_bf16 v[66:69], v[172:175], v[188:191], v[66:69]
	v_mfma_f32_16x16x32_bf16 v[70:73], v[180:183], v[188:191], v[70:73]
	v_mfma_f32_16x16x32_bf16 v[74:77], v[172:175], v[196:199], v[74:77]
	v_mfma_f32_16x16x32_bf16 v[78:81], v[180:183], v[196:199], v[78:81]
	v_mfma_f32_16x16x32_bf16 v[82:85], v[172:175], v[204:207], v[82:85]
	v_mfma_f32_16x16x32_bf16 v[86:89], v[180:183], v[204:207], v[86:89]
	v_mfma_f32_16x16x32_bf16 v[90:93], v[172:175], v[212:215], v[90:93]
	v_mfma_f32_16x16x32_bf16 v[98:101], v[180:183], v[212:215], v[98:101]
	s_barrier
; #define G_STAGE(bufoff, gbase, voff) do { _Pragma("unroll") for (int _i = 0; _i < 2; ++_i) \
;     __builtin_amdgcn_global_load_lds((const unsigned*)((const char*)(gbase) + (voff)[_i]), (LAS unsigned*)(lds + (bufoff) + ldsw + _i * 8192), 16, 0, 0); } while (0)
; #define G_LDA(dst, b, h) do { _Pragma("unroll") for (int m = 0; m < 4; ++m) _Pragma("unroll") for (int k = 0; k < 2; ++k) dst[m][k] = *(const LAS bf16x8*)(lds + G_SA(b, h) + aoff + m * 2048 + k * 1024); } while (0)
; #define G_LDB(dst, b, h) do { _Pragma("unroll") for (int n = 0; n < 2; ++n) _Pragma("unroll") for (int k = 0; k < 2; ++k) dst[n][k] = *(const LAS bf16x8*)(lds + G_SB(b, h) + boff + n * 2048 + k * 1024); } while (0)
; #define G_MMA(ai, bj, At, Bt) do { __builtin_amdgcn_s_setprio(1); _Pragma("unroll") for (int m = 0; m < 4; ++m) _Pragma("unroll") for (int n = 0; n < 2; ++n) _Pragma("unroll") for (int k = 0; k < 2; ++k) \
;     acc[ai][bj][m][n] = __builtin_amdgcn_mfma_f32_16x16x32_bf16(Bt[n][k], At[m][k], acc[ai][bj][m][n], 0, 0, 0); __builtin_amdgcn_s_setprio(0); } while (0)
; #define G_WAIT_V(n) asm volatile("s_waitcnt vmcnt(" #n ")" ::: "memory")
; #define G_WAIT_L(n) asm volatile("s_waitcnt lgkmcnt(" #n ")" ::: "memory")
; #define G_BAR __builtin_amdgcn_s_barrier()
; #define G_SCHED __builtin_amdgcn_sched_barrier(0)
; template <int GP> DI void gemm_phase(const Params& p, int l, int which, char* smem, int wv) {
;     ...
;       G_LDB(B0, 0, 0); G_SCHED; G_LDA(At, 0, 0); G_STAGE(G_SA(1, 1), a1 + hstep, voffA);
;       G_WAIT_L(8); G_BAR; G_WAIT_L(0); G_MMA(0, 0, At, B0); G_BAR; G_SCHED;
;       G_LDB(B1, 0, 1); G_STAGE(G_SB(0, 0), b2, vb0);
;       G_BAR; G_WAIT_L(0); G_MMA(0, 1, At, B1); G_BAR;
;       G_LDA(At, 0, 1); G_STAGE(G_SA(0, 0), a2, voffA);
;       G_BAR; G_WAIT_L(0); G_MMA(1, 0, At, B0); G_BAR; G_SCHED;
;       G_STAGE(G_SB(0, 1), b2, vb1);
;       G_WAIT_V(6); G_BAR; G_MMA(1, 1, At, B1); G_BAR;
;       G_LDB(B0, 1, 0); G_SCHED; G_LDA(At, 1, 0); G_STAGE(G_SA(0, 1), a2 + hstep, voffA);
;       G_WAIT_L(8); G_BAR; G_WAIT_L(0); G_MMA(0, 0, At, B0); G_BAR; G_SCHED;
;       G_LDB(B1, 1, 1); G_STAGE(G_SB(1, 0), b3, vb0);
;       G_BAR; G_WAIT_L(0); G_MMA(0, 1, At, B1); G_BAR;
;       G_LDA(At, 1, 1); G_STAGE(G_SA(1, 0), a3, voffA);
;       G_BAR; G_WAIT_L(0); G_MMA(1, 0, At, B0); G_BAR; G_SCHED;
;       G_STAGE(G_SB(1, 1), b3, vb1);
;       G_WAIT_V(6); G_BAR; G_MMA(1, 1, At, B1); G_BAR;
	s_mov_b32 m0, s41
	v_mov_b32_e32 v135, v1
	global_load_lds_dwordx4 v134, s[28:29]
	s_mov_b32 m0, s42
	v_mov_b32_e32 v155, v1
	global_load_lds_dwordx4 v154, s[28:29]
	s_waitcnt vmcnt(6)
	v_lshl_add_u64 v[246:247], s[28:29], 0, v[134:135]
	v_lshl_add_u64 v[248:249], s[28:29], 0, v[154:155]
	s_barrier
	v_mfma_f32_16x16x32_bf16 v[94:97], v[216:219], v[184:187], v[94:97]
	v_mfma_f32_16x16x32_bf16 v[102:105], v[224:227], v[184:187], v[102:105]
	v_mfma_f32_16x16x32_bf16 v[106:109], v[216:219], v[192:195], v[106:109]
	v_mfma_f32_16x16x32_bf16 v[110:113], v[224:227], v[192:195], v[110:113]
	v_mfma_f32_16x16x32_bf16 v[114:117], v[216:219], v[200:203], v[114:117]
	v_mfma_f32_16x16x32_bf16 v[118:121], v[224:227], v[200:203], v[118:121]
	v_mfma_f32_16x16x32_bf16 v[122:125], v[216:219], v[208:211], v[122:125]
	v_mfma_f32_16x16x32_bf16 v[126:129], v[224:227], v[208:211], v[126:129]
	v_mfma_f32_16x16x32_bf16 v[94:97], v[220:223], v[188:191], v[94:97]
	v_mfma_f32_16x16x32_bf16 v[102:105], v[238:241], v[188:191], v[102:105]
	v_mfma_f32_16x16x32_bf16 v[106:109], v[220:223], v[196:199], v[106:109]
	v_mfma_f32_16x16x32_bf16 v[110:113], v[238:241], v[196:199], v[110:113]
	v_mfma_f32_16x16x32_bf16 v[114:117], v[220:223], v[204:207], v[114:117]
	v_mfma_f32_16x16x32_bf16 v[118:121], v[238:241], v[204:207], v[118:121]
	v_mfma_f32_16x16x32_bf16 v[122:125], v[220:223], v[212:215], v[122:125]
	v_mfma_f32_16x16x32_bf16 v[126:129], v[238:241], v[212:215], v[126:129]
	v_add_u32_e32 v135, 0x18000, v166
	s_barrier
	ds_read_b128 v[168:171], v135
	ds_read_b128 v[172:175], v135 offset:1024
	ds_read_b128 v[176:179], v135 offset:2048
	ds_read_b128 v[180:183], v135 offset:3072
	s_add_u32 s28, s30, 0x80000
	s_addc_u32 s29, s31, 0
	s_mov_b32 m0, s43
	v_lshl_add_u64 v[216:217], s[28:29], 0, v[130:131]
	ds_read_b128 v[184:187], v165 offset:32768
	ds_read_b128 v[188:191], v165 offset:33792
	ds_read_b128 v[192:195], v165 offset:34816
	ds_read_b128 v[196:199], v165 offset:35840
	ds_read_b128 v[200:203], v165 offset:36864
	ds_read_b128 v[204:207], v165 offset:37888
	ds_read_b128 v[208:211], v165 offset:38912
	ds_read_b128 v[212:215], v165 offset:39936
	global_load_lds_dwordx4 v[216:217], off
	v_lshl_add_u64 v[216:217], s[28:29], 0, v[132:133]
	s_mov_b32 m0, s44
	s_nop 0
	global_load_lds_dwordx4 v[216:217], off
	s_waitcnt lgkmcnt(8)
	s_barrier
	s_waitcnt lgkmcnt(0)
	s_waitcnt lgkmcnt(0)
	v_mfma_f32_16x16x32_bf16 v[62:65], v[168:171], v[184:187], v[62:65]
	v_mfma_f32_16x16x32_bf16 v[58:61], v[176:179], v[184:187], v[58:61]
	v_mfma_f32_16x16x32_bf16 v[54:57], v[168:171], v[192:195], v[54:57]
	v_mfma_f32_16x16x32_bf16 v[50:53], v[176:179], v[192:195], v[50:53]
	v_mfma_f32_16x16x32_bf16 v[46:49], v[168:171], v[200:203], v[46:49]
	v_mfma_f32_16x16x32_bf16 v[42:45], v[176:179], v[200:203], v[42:45]
	v_mfma_f32_16x16x32_bf16 v[38:41], v[168:171], v[208:211], v[38:41]
	v_mfma_f32_16x16x32_bf16 v[34:37], v[176:179], v[208:211], v[34:37]
	v_mfma_f32_16x16x32_bf16 v[62:65], v[172:175], v[188:191], v[62:65]
	v_mfma_f32_16x16x32_bf16 v[58:61], v[180:183], v[188:191], v[58:61]
	v_mfma_f32_16x16x32_bf16 v[54:57], v[172:175], v[196:199], v[54:57]
	v_mfma_f32_16x16x32_bf16 v[50:53], v[180:183], v[196:199], v[50:53]
	v_mfma_f32_16x16x32_bf16 v[46:49], v[172:175], v[204:207], v[46:49]
	v_mfma_f32_16x16x32_bf16 v[42:45], v[180:183], v[204:207], v[42:45]
	v_mfma_f32_16x16x32_bf16 v[38:41], v[172:175], v[212:215], v[38:41]
	v_mfma_f32_16x16x32_bf16 v[34:37], v[180:183], v[212:215], v[34:37]
	s_barrier
	s_mov_b32 m0, s45
	v_add_u32_e32 v135, 0x1c000, v166
	v_lshl_add_u64 v[228:229], v[228:229], 0, s[74:75]
	ds_read_b128 v[216:219], v135
	ds_read_b128 v[220:223], v135 offset:1024
	ds_read_b128 v[224:227], v135 offset:2048
	ds_read_b128 v[238:241], v135 offset:3072
	global_load_lds_dwordx4 v[228:229], off
	v_lshl_add_u64 v[228:229], v[234:235], 0, s[74:75]
	s_mov_b32 m0, s46
	s_nop 0
	global_load_lds_dwordx4 v[228:229], off
	s_barrier
; #define G_STAGE(bufoff, gbase, voff) do { _Pragma("unroll") for (int _i = 0; _i < 2; ++_i) \
;     __builtin_amdgcn_global_load_lds((const unsigned*)((const char*)(gbase) + (voff)[_i]), (LAS unsigned*)(lds + (bufoff) + ldsw + _i * 8192), 16, 0, 0); } while (0)
; #define G_LDA(dst, b, h) do { _Pragma("unroll") for (int m = 0; m < 4; ++m) _Pragma("unroll") for (int k = 0; k < 2; ++k) dst[m][k] = *(const LAS bf16x8*)(lds + G_SA(b, h) + aoff + m * 2048 + k * 1024); } while (0)
; #define G_LDB(dst, b, h) do { _Pragma("unroll") for (int n = 0; n < 2; ++n) _Pragma("unroll") for (int k = 0; k < 2; ++k) dst[n][k] = *(const LAS bf16x8*)(lds + G_SB(b, h) + boff + n * 2048 + k * 1024); } while (0)
; #define G_MMA(ai, bj, At, Bt) do { __builtin_amdgcn_s_setprio(1); _Pragma("unroll") for (int m = 0; m < 4; ++m) _Pragma("unroll") for (int n = 0; n < 2; ++n) _Pragma("unroll") for (int k = 0; k < 2; ++k) \
;     acc[ai][bj][m][n] = __builtin_amdgcn_mfma_f32_16x16x32_bf16(Bt[n][k], At[m][k], acc[ai][bj][m][n], 0, 0, 0); __builtin_amdgcn_s_setprio(0); } while (0)
; #define G_WAIT_V(n) asm volatile("s_waitcnt vmcnt(" #n ")" ::: "memory")
; #define G_WAIT_L(n) asm volatile("s_waitcnt lgkmcnt(" #n ")" ::: "memory")
; #define G_BAR __builtin_amdgcn_s_barrier()
; #define G_SCHED __builtin_amdgcn_sched_barrier(0)
; template <int GP> DI void gemm_phase(const Params& p, int l, int which, char* smem, int wv) {
;     ...
;       G_WAIT_V(6); G_BAR; G_MMA(1, 1, At, B1); G_BAR;
;       G_LDB(B0, 1, 0); G_SCHED; G_LDA(At, 1, 0); G_STAGE(G_SA(0, 1), a2 + hstep, voffA);
;       G_WAIT_L(8); G_BAR; G_WAIT_L(0); G_MMA(0, 0, At, B0); G_BAR; G_SCHED;
;       G_LDB(B1, 1, 1); G_STAGE(G_SB(1, 0), b3, vb0);
;       G_BAR; G_WAIT_L(0); G_MMA(0, 1, At, B1); G_BAR;
;       G_LDA(At, 1, 1); G_STAGE(G_SA(1, 0), a3, voffA);
;       G_BAR; G_WAIT_L(0); G_MMA(1, 0, At, B0); G_BAR; G_SCHED;
;       G_STAGE(G_SB(1, 1), b3, vb1);
;       G_WAIT_V(6); G_BAR; G_MMA(1, 1, At, B1); G_BAR;
;     }
;     if (GP == 0) {
;       const int m0 = cmt * 256, n0 = cnt_ * 256;
;       const bool isctx = (cmt % 9) == 0;
	s_waitcnt lgkmcnt(0)
	s_waitcnt lgkmcnt(0)
	v_mfma_f32_16x16x32_bf16 v[30:33], v[216:219], v[184:187], v[30:33]
	v_mfma_f32_16x16x32_bf16 v[26:29], v[224:227], v[184:187], v[26:29]
	v_mfma_f32_16x16x32_bf16 v[22:25], v[216:219], v[192:195], v[22:25]
	v_mfma_f32_16x16x32_bf16 v[18:21], v[224:227], v[192:195], v[18:21]
	v_mfma_f32_16x16x32_bf16 v[14:17], v[216:219], v[200:203], v[14:17]
	v_mfma_f32_16x16x32_bf16 v[10:13], v[224:227], v[200:203], v[10:13]
	v_mfma_f32_16x16x32_bf16 v[6:9], v[216:219], v[208:211], v[6:9]
	v_mfma_f32_16x16x32_bf16 v[2:5], v[224:227], v[208:211], v[2:5]
	v_mfma_f32_16x16x32_bf16 v[30:33], v[220:223], v[188:191], v[30:33]
	v_mfma_f32_16x16x32_bf16 v[26:29], v[238:241], v[188:191], v[26:29]
	v_mfma_f32_16x16x32_bf16 v[22:25], v[220:223], v[196:199], v[22:25]
	v_mfma_f32_16x16x32_bf16 v[18:21], v[238:241], v[196:199], v[18:21]
	v_mfma_f32_16x16x32_bf16 v[14:17], v[220:223], v[204:207], v[14:17]
	v_mfma_f32_16x16x32_bf16 v[10:13], v[238:241], v[204:207], v[10:13]
	v_mfma_f32_16x16x32_bf16 v[6:9], v[220:223], v[212:215], v[6:9]
	v_mfma_f32_16x16x32_bf16 v[2:5], v[238:241], v[212:215], v[2:5]
	s_mov_b32 m0, s48
	v_lshl_add_u64 v[228:229], v[242:243], 0, s[74:75]
	s_barrier
	ds_read_b128 v[184:187], v165 offset:49152
	ds_read_b128 v[188:191], v165 offset:50176
	ds_read_b128 v[192:195], v165 offset:51200
	ds_read_b128 v[196:199], v165 offset:52224
	ds_read_b128 v[200:203], v165 offset:53248
	ds_read_b128 v[204:207], v165 offset:54272
	ds_read_b128 v[208:211], v165 offset:55296
	ds_read_b128 v[212:215], v165 offset:56320
	global_load_lds_dwordx4 v[228:229], off
	v_lshl_add_u64 v[228:229], v[244:245], 0, s[74:75]
	s_mov_b32 m0, s49
	s_nop 0
	global_load_lds_dwordx4 v[228:229], off
	s_barrier
	s_waitcnt lgkmcnt(0)
	s_waitcnt lgkmcnt(0)
	v_mfma_f32_16x16x32_bf16 v[66:69], v[168:171], v[184:187], v[66:69]
	v_mfma_f32_16x16x32_bf16 v[70:73], v[176:179], v[184:187], v[70:73]
	v_mfma_f32_16x16x32_bf16 v[74:77], v[168:171], v[192:195], v[74:77]
	v_mfma_f32_16x16x32_bf16 v[78:81], v[176:179], v[192:195], v[78:81]
	v_mfma_f32_16x16x32_bf16 v[82:85], v[168:171], v[200:203], v[82:85]
	v_mfma_f32_16x16x32_bf16 v[86:89], v[176:179], v[200:203], v[86:89]
	v_mfma_f32_16x16x32_bf16 v[90:93], v[168:171], v[208:211], v[90:93]
	v_mfma_f32_16x16x32_bf16 v[98:101], v[176:179], v[208:211], v[98:101]
	v_mfma_f32_16x16x32_bf16 v[66:69], v[172:175], v[188:191], v[66:69]
	v_mfma_f32_16x16x32_bf16 v[70:73], v[180:183], v[188:191], v[70:73]
	v_mfma_f32_16x16x32_bf16 v[74:77], v[172:175], v[196:199], v[74:77]
	v_mfma_f32_16x16x32_bf16 v[78:81], v[180:183], v[196:199], v[78:81]
	v_mfma_f32_16x16x32_bf16 v[82:85], v[172:175], v[204:207], v[82:85]
	v_mfma_f32_16x16x32_bf16 v[86:89], v[180:183], v[204:207], v[86:89]
	v_mfma_f32_16x16x32_bf16 v[90:93], v[172:175], v[212:215], v[90:93]
	v_mfma_f32_16x16x32_bf16 v[98:101], v[180:183], v[212:215], v[98:101]
	s_barrier
	s_mov_b32 m0, s50
	v_lshl_add_u64 v[168:169], v[246:247], 0, s[74:75]
	global_load_lds_dwordx4 v[168:169], off
	v_lshl_add_u64 v[168:169], v[248:249], 0, s[74:75]
	s_mov_b32 m0, s52
	s_nop 0
	global_load_lds_dwordx4 v[168:169], off
	s_waitcnt vmcnt(6)
	s_barrier
	v_mfma_f32_16x16x32_bf16 v[94:97], v[216:219], v[184:187], v[94:97]
	v_mfma_f32_16x16x32_bf16 v[102:105], v[224:227], v[184:187], v[102:105]
	v_mfma_f32_16x16x32_bf16 v[106:109], v[216:219], v[192:195], v[106:109]
	v_mfma_f32_16x16x32_bf16 v[110:113], v[224:227], v[192:195], v[110:113]
	v_mfma_f32_16x16x32_bf16 v[114:117], v[216:219], v[200:203], v[114:117]
	v_mfma_f32_16x16x32_bf16 v[118:121], v[224:227], v[200:203], v[118:121]
	v_mfma_f32_16x16x32_bf16 v[122:125], v[216:219], v[208:211], v[122:125]
	v_mfma_f32_16x16x32_bf16 v[126:129], v[224:227], v[208:211], v[126:129]
	v_mfma_f32_16x16x32_bf16 v[94:97], v[220:223], v[188:191], v[94:97]
	v_mfma_f32_16x16x32_bf16 v[102:105], v[238:241], v[188:191], v[102:105]
	v_mfma_f32_16x16x32_bf16 v[106:109], v[220:223], v[196:199], v[106:109]
	v_mfma_f32_16x16x32_bf16 v[110:113], v[238:241], v[196:199], v[110:113]
	v_mfma_f32_16x16x32_bf16 v[114:117], v[220:223], v[204:207], v[114:117]
	v_mfma_f32_16x16x32_bf16 v[118:121], v[238:241], v[204:207], v[118:121]
	v_mfma_f32_16x16x32_bf16 v[122:125], v[220:223], v[212:215], v[122:125]
	v_mfma_f32_16x16x32_bf16 v[126:129], v[238:241], v[212:215], v[126:129]
	s_add_i32 s28, s60, 2
	s_add_u32 s26, s26, 0x100
	s_addc_u32 s27, s27, 0
	v_lshl_add_u64 v[162:163], v[162:163], 0, s[78:79]
	s_cmp_ge_i32 s60, s36
	v_lshl_add_u64 v[160:161], v[160:161], 0, s[78:79]
	s_barrier
	s_cbranch_scc0 .LBB0_147
	s_mul_hi_i32 s11, s2, 0x38e38e39
	s_lshr_b32 s26, s11, 31
	s_ashr_i32 s11, s11, 1
	s_add_i32 s26, s11, s26
	s_mul_i32 s11, s26, 9
	s_sub_i32 s11, s2, s11
	s_cmp_lg_u32 s11, 0
	s_cbranch_scc0 .LBB0_155
	s_lshl_b32 s28, s2, 8
	s_ashr_i32 s29, s28, 31
	s_lshl_b64 s[28:29], s[28:29], 12
	s_add_u32 s28, s94, s28
	s_addc_u32 s29, s95, s29
	s_cbranch_execnz .LBB0_153

; #define G_STAGE(bufoff, gbase, voff) do { _Pragma("unroll") for (int _i = 0; _i < 2; ++_i) \
;     __builtin_amdgcn_global_load_lds((const unsigned*)((const char*)(gbase) + (voff)[_i]), (LAS unsigned*)(lds + (bufoff) + ldsw + _i * 8192), 16, 0, 0); } while (0)
; #define G_LDA(dst, b, h) do { _Pragma("unroll") for (int m = 0; m < 4; ++m) _Pragma("unroll") for (int k = 0; k < 2; ++k) dst[m][k] = *(const LAS bf16x8*)(lds + G_SA(b, h) + aoff + m * 2048 + k * 1024); } while (0)
; #define G_LDB(dst, b, h) do { _Pragma("unroll") for (int n = 0; n < 2; ++n) _Pragma("unroll") for (int k = 0; k < 2; ++k) dst[n][k] = *(const LAS bf16x8*)(lds + G_SB(b, h) + boff + n * 2048 + k * 1024); } while (0)
; #define G_MMA(ai, bj, At, Bt) do { __builtin_amdgcn_s_setprio(1); _Pragma("unroll") for (int m = 0; m < 4; ++m) _Pragma("unroll") for (int n = 0; n < 2; ++n) _Pragma("unroll") for (int k = 0; k < 2; ++k) \
;     acc[ai][bj][m][n] = __builtin_amdgcn_mfma_f32_16x16x32_bf16(Bt[n][k], At[m][k], acc[ai][bj][m][n], 0, 0, 0); __builtin_amdgcn_s_setprio(0); } while (0)
; #define G_WAIT_V(n) asm volatile("s_waitcnt vmcnt(" #n ")" ::: "memory")
; #define G_WAIT_L(n) asm volatile("s_waitcnt lgkmcnt(" #n ")" ::: "memory")
; #define G_BAR __builtin_amdgcn_s_barrier()
; #define G_SCHED __builtin_amdgcn_sched_barrier(0)
; template <int GP> DI void gemm_phase(const Params& p, int l, int which, char* smem, int wv) {
;     ...
;       G_LDB(B0, 0, 0); G_SCHED; G_LDA(At, 0, 0); G_STAGE(G_SA(1, 1), a1 + hstep, voffA);
;       G_WAIT_L(8); G_BAR; G_WAIT_L(0); G_MMA(0, 0, At, B0); G_BAR; G_SCHED;
;       G_LDB(B1, 0, 1); G_STAGE(G_SB(0, 0), b2, vb0);
;       G_BAR; G_WAIT_L(0); G_MMA(0, 1, At, B1); G_BAR;
;       G_LDA(At, 0, 1); G_STAGE(G_SA(0, 0), a2, voffA);
;       G_BAR; G_WAIT_L(0); G_MMA(1, 0, At, B0); G_BAR; G_SCHED;
;       G_STAGE(G_SB(0, 1), b2, vb1);
;       G_WAIT_V(6); G_BAR; G_MMA(1, 1, At, B1); G_BAR;
;       G_LDB(B0, 1, 0); G_SCHED; G_LDA(At, 1, 0); G_STAGE(G_SA(0, 1), a2 + hstep, voffA);
;       G_WAIT_L(8); G_BAR; G_WAIT_L(0); G_MMA(0, 0, At, B0); G_BAR; G_SCHED;
;       G_LDB(B1, 1, 1); G_STAGE(G_SB(1, 0), b3, vb0);
;       G_BAR; G_WAIT_L(0); G_MMA(0, 1, At, B1); G_BAR;
;       G_LDA(At, 1, 1); G_STAGE(G_SA(1, 0), a3, voffA);
;       G_BAR; G_WAIT_L(0); G_MMA(1, 0, At, B0); G_BAR; G_SCHED;
;       G_STAGE(G_SB(1, 1), b3, vb1);
;       G_WAIT_V(6); G_BAR; G_MMA(1, 1, At, B1); G_BAR;
.LBB0_209:
	s_add_u32 s8, s28, s2
	v_add_u32_e32 v131, 0x10000, v212
	s_addc_u32 s9, s29, s3
	ds_read_b128 v[148:151], v131
	ds_read_b128 v[152:155], v131 offset:1024
	ds_read_b128 v[156:159], v131 offset:2048
	ds_read_b128 v[160:163], v131 offset:3072
	s_add_u32 s52, s8, 0x100
	s_addc_u32 s53, s9, 0
	s_and_b64 s[8:9], s[6:7], exec
	s_cselect_b32 s9, s10, s53
	s_cselect_b32 s8, s11, s52
	s_add_u32 s52, s74, s2
	s_addc_u32 s53, s75, s3
	s_and_b64 s[6:7], s[6:7], exec
	s_cselect_b32 s7, s37, s53
	s_cselect_b32 s6, s39, s52
	v_lshl_add_u64 v[196:197], v[144:145], 0, s[2:3]
	s_add_i32 m0, s23, 0xc000
	ds_read_b128 v[164:167], v211
	ds_read_b128 v[168:171], v211 offset:1024
	ds_read_b128 v[172:175], v211 offset:2048
	ds_read_b128 v[176:179], v211 offset:3072
	ds_read_b128 v[180:183], v211 offset:4096
	ds_read_b128 v[184:187], v211 offset:5120
	ds_read_b128 v[188:191], v211 offset:6144
	ds_read_b128 v[192:195], v211 offset:7168
	global_load_lds_dwordx4 v[196:197], off
	v_lshl_add_u64 v[196:197], v[146:147], 0, s[2:3]
	s_add_i32 m0, s23, 0xe000
	s_nop 0
	global_load_lds_dwordx4 v[196:197], off
	s_waitcnt lgkmcnt(8)
	s_barrier
	s_waitcnt lgkmcnt(0)
	s_waitcnt lgkmcnt(0)
	v_mfma_f32_16x16x32_bf16 v[62:65], v[148:151], v[164:167], v[62:65]
	v_mfma_f32_16x16x32_bf16 v[58:61], v[156:159], v[164:167], v[58:61]
	v_mfma_f32_16x16x32_bf16 v[54:57], v[148:151], v[172:175], v[54:57]
	v_mfma_f32_16x16x32_bf16 v[50:53], v[156:159], v[172:175], v[50:53]
	v_mfma_f32_16x16x32_bf16 v[46:49], v[148:151], v[180:183], v[46:49]
	v_mfma_f32_16x16x32_bf16 v[42:45], v[156:159], v[180:183], v[42:45]
	v_mfma_f32_16x16x32_bf16 v[38:41], v[148:151], v[188:191], v[38:41]
	v_mfma_f32_16x16x32_bf16 v[34:37], v[156:159], v[188:191], v[34:37]
	v_mfma_f32_16x16x32_bf16 v[62:65], v[152:155], v[168:171], v[62:65]
	v_mfma_f32_16x16x32_bf16 v[58:61], v[160:163], v[168:171], v[58:61]
	v_mfma_f32_16x16x32_bf16 v[54:57], v[152:155], v[176:179], v[54:57]
	v_mfma_f32_16x16x32_bf16 v[50:53], v[160:163], v[176:179], v[50:53]
	v_mfma_f32_16x16x32_bf16 v[46:49], v[152:155], v[184:187], v[46:49]
	v_mfma_f32_16x16x32_bf16 v[42:45], v[160:163], v[184:187], v[42:45]
	v_mfma_f32_16x16x32_bf16 v[38:41], v[152:155], v[192:195], v[38:41]
	v_mfma_f32_16x16x32_bf16 v[34:37], v[160:163], v[192:195], v[34:37]
	s_barrier
	s_mov_b32 m0, s25
	v_add_u32_e32 v131, 0x14000, v212
	ds_read_b128 v[196:199], v131
	ds_read_b128 v[200:203], v131 offset:1024
	ds_read_b128 v[204:207], v131 offset:2048
	ds_read_b128 v[238:241], v131 offset:3072
	global_load_lds_dwordx4 v0, s[6:7]
	s_mov_b32 m0, s58
	v_mov_b32_e32 v137, v1
	global_load_lds_dwordx4 v136, s[6:7]
	s_barrier
	s_waitcnt lgkmcnt(0)
	v_lshl_add_u64 v[228:229], s[6:7], 0, v[0:1]
	v_lshl_add_u64 v[234:235], s[6:7], 0, v[136:137]
	s_waitcnt lgkmcnt(0)
	v_mfma_f32_16x16x32_bf16 v[30:33], v[196:199], v[164:167], v[30:33]
	v_mfma_f32_16x16x32_bf16 v[26:29], v[204:207], v[164:167], v[26:29]
	v_mfma_f32_16x16x32_bf16 v[22:25], v[196:199], v[172:175], v[22:25]
	v_mfma_f32_16x16x32_bf16 v[18:21], v[204:207], v[172:175], v[18:21]
	v_mfma_f32_16x16x32_bf16 v[14:17], v[196:199], v[180:183], v[14:17]
	v_mfma_f32_16x16x32_bf16 v[10:13], v[204:207], v[180:183], v[10:13]
	v_mfma_f32_16x16x32_bf16 v[6:9], v[196:199], v[188:191], v[6:9]
	v_mfma_f32_16x16x32_bf16 v[2:5], v[204:207], v[188:191], v[2:5]
	v_mfma_f32_16x16x32_bf16 v[30:33], v[200:203], v[168:171], v[30:33]
	v_mfma_f32_16x16x32_bf16 v[26:29], v[238:241], v[168:171], v[26:29]
	v_mfma_f32_16x16x32_bf16 v[22:25], v[200:203], v[176:179], v[22:25]
	v_mfma_f32_16x16x32_bf16 v[18:21], v[238:241], v[176:179], v[18:21]
	v_mfma_f32_16x16x32_bf16 v[14:17], v[200:203], v[184:187], v[14:17]
	v_mfma_f32_16x16x32_bf16 v[10:13], v[238:241], v[184:187], v[10:13]
	v_mfma_f32_16x16x32_bf16 v[6:9], v[200:203], v[192:195], v[6:9]
	v_mfma_f32_16x16x32_bf16 v[2:5], v[238:241], v[192:195], v[2:5]
	s_mov_b32 m0, s23
	v_lshl_add_u64 v[242:243], s[8:9], 0, v[132:133]
	s_barrier
	ds_read_b128 v[164:167], v211 offset:16384
	ds_read_b128 v[168:171], v211 offset:17408
	ds_read_b128 v[172:175], v211 offset:18432
	ds_read_b128 v[176:179], v211 offset:19456
	ds_read_b128 v[180:183], v211 offset:20480
	ds_read_b128 v[184:187], v211 offset:21504
	ds_read_b128 v[188:191], v211 offset:22528
	ds_read_b128 v[192:195], v211 offset:23552
	global_load_lds_dwordx4 v[242:243], off
	v_lshl_add_u64 v[244:245], s[8:9], 0, v[134:135]
	s_mov_b32 m0, s59
	s_nop 0
	global_load_lds_dwordx4 v[244:245], off
	s_barrier
	s_waitcnt lgkmcnt(0)
	s_waitcnt lgkmcnt(0)
	v_mfma_f32_16x16x32_bf16 v[66:69], v[148:151], v[164:167], v[66:69]
	v_mfma_f32_16x16x32_bf16 v[70:73], v[156:159], v[164:167], v[70:73]
	v_mfma_f32_16x16x32_bf16 v[74:77], v[148:151], v[172:175], v[74:77]
	v_mfma_f32_16x16x32_bf16 v[78:81], v[156:159], v[172:175], v[78:81]
	v_mfma_f32_16x16x32_bf16 v[82:85], v[148:151], v[180:183], v[82:85]
	v_mfma_f32_16x16x32_bf16 v[86:89], v[156:159], v[180:183], v[86:89]
	v_mfma_f32_16x16x32_bf16 v[90:93], v[148:151], v[188:191], v[90:93]
	v_mfma_f32_16x16x32_bf16 v[94:97], v[156:159], v[188:191], v[94:97]
	v_mfma_f32_16x16x32_bf16 v[66:69], v[152:155], v[168:171], v[66:69]
	v_mfma_f32_16x16x32_bf16 v[70:73], v[160:163], v[168:171], v[70:73]
	v_mfma_f32_16x16x32_bf16 v[74:77], v[152:155], v[176:179], v[74:77]
	v_mfma_f32_16x16x32_bf16 v[78:81], v[160:163], v[176:179], v[78:81]
	v_mfma_f32_16x16x32_bf16 v[82:85], v[152:155], v[184:187], v[82:85]
	v_mfma_f32_16x16x32_bf16 v[86:89], v[160:163], v[184:187], v[86:89]
	v_mfma_f32_16x16x32_bf16 v[90:93], v[152:155], v[192:195], v[90:93]
	v_mfma_f32_16x16x32_bf16 v[94:97], v[160:163], v[192:195], v[94:97]
	s_barrier
; #define G_STAGE(bufoff, gbase, voff) do { _Pragma("unroll") for (int _i = 0; _i < 2; ++_i) \
;     __builtin_amdgcn_global_load_lds((const unsigned*)((const char*)(gbase) + (voff)[_i]), (LAS unsigned*)(lds + (bufoff) + ldsw + _i * 8192), 16, 0, 0); } while (0)
; #define G_LDA(dst, b, h) do { _Pragma("unroll") for (int m = 0; m < 4; ++m) _Pragma("unroll") for (int k = 0; k < 2; ++k) dst[m][k] = *(const LAS bf16x8*)(lds + G_SA(b, h) + aoff + m * 2048 + k * 1024); } while (0)
; #define G_LDB(dst, b, h) do { _Pragma("unroll") for (int n = 0; n < 2; ++n) _Pragma("unroll") for (int k = 0; k < 2; ++k) dst[n][k] = *(const LAS bf16x8*)(lds + G_SB(b, h) + boff + n * 2048 + k * 1024); } while (0)
; #define G_MMA(ai, bj, At, Bt) do { __builtin_amdgcn_s_setprio(1); _Pragma("unroll") for (int m = 0; m < 4; ++m) _Pragma("unroll") for (int n = 0; n < 2; ++n) _Pragma("unroll") for (int k = 0; k < 2; ++k) \
;     acc[ai][bj][m][n] = __builtin_amdgcn_mfma_f32_16x16x32_bf16(Bt[n][k], At[m][k], acc[ai][bj][m][n], 0, 0, 0); __builtin_amdgcn_s_setprio(0); } while (0)
; #define G_WAIT_V(n) asm volatile("s_waitcnt vmcnt(" #n ")" ::: "memory")
; #define G_WAIT_L(n) asm volatile("s_waitcnt lgkmcnt(" #n ")" ::: "memory")
; #define G_BAR __builtin_amdgcn_s_barrier()
; #define G_SCHED __builtin_amdgcn_sched_barrier(0)
; template <int GP> DI void gemm_phase(const Params& p, int l, int which, char* smem, int wv) {
;     ...
;       G_STAGE(G_SB(0, 1), b2, vb1);
;       G_WAIT_V(6); G_BAR; G_MMA(1, 1, At, B1); G_BAR;
;       G_LDB(B0, 1, 0); G_SCHED; G_LDA(At, 1, 0); G_STAGE(G_SA(0, 1), a2 + hstep, voffA);
;       G_WAIT_L(8); G_BAR; G_WAIT_L(0); G_MMA(0, 0, At, B0); G_BAR; G_SCHED;
;       G_LDB(B1, 1, 1); G_STAGE(G_SB(1, 0), b3, vb0);
	s_mov_b32 m0, s60
	v_mov_b32_e32 v131, v1
	global_load_lds_dwordx4 v130, s[6:7]
	s_mov_b32 m0, s61
	v_mov_b32_e32 v143, v1
	global_load_lds_dwordx4 v142, s[6:7]
	s_waitcnt vmcnt(6)
	v_lshl_add_u64 v[246:247], s[6:7], 0, v[130:131]
	v_lshl_add_u64 v[248:249], s[6:7], 0, v[142:143]
	s_barrier
	v_mfma_f32_16x16x32_bf16 v[98:101], v[196:199], v[164:167], v[98:101]
	v_mfma_f32_16x16x32_bf16 v[102:105], v[204:207], v[164:167], v[102:105]
	v_mfma_f32_16x16x32_bf16 v[106:109], v[196:199], v[172:175], v[106:109]
	v_mfma_f32_16x16x32_bf16 v[110:113], v[204:207], v[172:175], v[110:113]
	v_mfma_f32_16x16x32_bf16 v[114:117], v[196:199], v[180:183], v[114:117]
	v_mfma_f32_16x16x32_bf16 v[118:121], v[204:207], v[180:183], v[118:121]
	v_mfma_f32_16x16x32_bf16 v[122:125], v[196:199], v[188:191], v[122:125]
	v_mfma_f32_16x16x32_bf16 v[126:129], v[204:207], v[188:191], v[126:129]
	v_mfma_f32_16x16x32_bf16 v[98:101], v[200:203], v[168:171], v[98:101]
	v_mfma_f32_16x16x32_bf16 v[102:105], v[238:241], v[168:171], v[102:105]
	v_mfma_f32_16x16x32_bf16 v[106:109], v[200:203], v[176:179], v[106:109]
	v_mfma_f32_16x16x32_bf16 v[110:113], v[238:241], v[176:179], v[110:113]
	v_mfma_f32_16x16x32_bf16 v[114:117], v[200:203], v[184:187], v[114:117]
	v_mfma_f32_16x16x32_bf16 v[118:121], v[238:241], v[184:187], v[118:121]
	v_mfma_f32_16x16x32_bf16 v[122:125], v[200:203], v[192:195], v[122:125]
	v_mfma_f32_16x16x32_bf16 v[126:129], v[238:241], v[192:195], v[126:129]
	v_add_u32_e32 v131, 0x18000, v212
	s_barrier
	ds_read_b128 v[148:151], v131
	ds_read_b128 v[152:155], v131 offset:1024
	ds_read_b128 v[156:159], v131 offset:2048
	ds_read_b128 v[160:163], v131 offset:3072
	s_add_u32 s6, s8, 0x80000
	s_addc_u32 s7, s9, 0
	s_mov_b32 m0, s62
	v_lshl_add_u64 v[196:197], s[6:7], 0, v[132:133]
	ds_read_b128 v[164:167], v211 offset:32768
	ds_read_b128 v[168:171], v211 offset:33792
	ds_read_b128 v[172:175], v211 offset:34816
	ds_read_b128 v[176:179], v211 offset:35840
	ds_read_b128 v[180:183], v211 offset:36864
	ds_read_b128 v[184:187], v211 offset:37888
	ds_read_b128 v[188:191], v211 offset:38912
	ds_read_b128 v[192:195], v211 offset:39936
	global_load_lds_dwordx4 v[196:197], off
	v_lshl_add_u64 v[196:197], s[6:7], 0, v[134:135]
	s_mov_b32 m0, s63
	s_nop 0
	global_load_lds_dwordx4 v[196:197], off
	s_waitcnt lgkmcnt(8)
	s_barrier
	s_waitcnt lgkmcnt(0)
	s_waitcnt lgkmcnt(0)
	v_mfma_f32_16x16x32_bf16 v[62:65], v[148:151], v[164:167], v[62:65]
	v_mfma_f32_16x16x32_bf16 v[58:61], v[156:159], v[164:167], v[58:61]
	v_mfma_f32_16x16x32_bf16 v[54:57], v[148:151], v[172:175], v[54:57]
	v_mfma_f32_16x16x32_bf16 v[50:53], v[156:159], v[172:175], v[50:53]
	v_mfma_f32_16x16x32_bf16 v[46:49], v[148:151], v[180:183], v[46:49]
	v_mfma_f32_16x16x32_bf16 v[42:45], v[156:159], v[180:183], v[42:45]
	v_mfma_f32_16x16x32_bf16 v[38:41], v[148:151], v[188:191], v[38:41]
	v_mfma_f32_16x16x32_bf16 v[34:37], v[156:159], v[188:191], v[34:37]
	v_mfma_f32_16x16x32_bf16 v[62:65], v[152:155], v[168:171], v[62:65]
	v_mfma_f32_16x16x32_bf16 v[58:61], v[160:163], v[168:171], v[58:61]
	v_mfma_f32_16x16x32_bf16 v[54:57], v[152:155], v[176:179], v[54:57]
	v_mfma_f32_16x16x32_bf16 v[50:53], v[160:163], v[176:179], v[50:53]
	v_mfma_f32_16x16x32_bf16 v[46:49], v[152:155], v[184:187], v[46:49]
	v_mfma_f32_16x16x32_bf16 v[42:45], v[160:163], v[184:187], v[42:45]
	v_mfma_f32_16x16x32_bf16 v[38:41], v[152:155], v[192:195], v[38:41]
	v_mfma_f32_16x16x32_bf16 v[34:37], v[160:163], v[192:195], v[34:37]
	s_barrier
	s_mov_b32 m0, s21
	v_add_u32_e32 v131, 0x1c000, v212
	v_lshl_add_u64 v[228:229], v[228:229], 0, s[16:17]
	ds_read_b128 v[196:199], v131
	ds_read_b128 v[200:203], v131 offset:1024
	ds_read_b128 v[204:207], v131 offset:2048
	ds_read_b128 v[238:241], v131 offset:3072
	global_load_lds_dwordx4 v[228:229], off
	v_lshl_add_u64 v[228:229], v[234:235], 0, s[16:17]
	s_mov_b32 m0, s64
	s_nop 0
	global_load_lds_dwordx4 v[228:229], off
	s_barrier
; #define G_STAGE(bufoff, gbase, voff) do { _Pragma("unroll") for (int _i = 0; _i < 2; ++_i) \
;     __builtin_amdgcn_global_load_lds((const unsigned*)((const char*)(gbase) + (voff)[_i]), (LAS unsigned*)(lds + (bufoff) + ldsw + _i * 8192), 16, 0, 0); } while (0)
; #define G_LDA(dst, b, h) do { _Pragma("unroll") for (int m = 0; m < 4; ++m) _Pragma("unroll") for (int k = 0; k < 2; ++k) dst[m][k] = *(const LAS bf16x8*)(lds + G_SA(b, h) + aoff + m * 2048 + k * 1024); } while (0)
; #define G_MMA(ai, bj, At, Bt) do { __builtin_amdgcn_s_setprio(1); _Pragma("unroll") for (int m = 0; m < 4; ++m) _Pragma("unroll") for (int n = 0; n < 2; ++n) _Pragma("unroll") for (int k = 0; k < 2; ++k) \
;     acc[ai][bj][m][n] = __builtin_amdgcn_mfma_f32_16x16x32_bf16(Bt[n][k], At[m][k], acc[ai][bj][m][n], 0, 0, 0); __builtin_amdgcn_s_setprio(0); } while (0)
; #define G_WAIT_V(n) asm volatile("s_waitcnt vmcnt(" #n ")" ::: "memory")
; #define G_WAIT_L(n) asm volatile("s_waitcnt lgkmcnt(" #n ")" ::: "memory")
; #define G_BAR __builtin_amdgcn_s_barrier()
; #define G_SCHED __builtin_amdgcn_sched_barrier(0)
; template <int GP> DI void gemm_phase(const Params& p, int l, int which, char* smem, int wv) {
;     ...
;       G_BAR; G_WAIT_L(0); G_MMA(0, 1, At, B1); G_BAR;
;       G_LDA(At, 1, 1); G_STAGE(G_SA(1, 0), a3, voffA);
;       G_BAR; G_WAIT_L(0); G_MMA(1, 0, At, B0); G_BAR; G_SCHED;
;       G_STAGE(G_SB(1, 1), b3, vb1);
;       G_WAIT_V(6); G_BAR; G_MMA(1, 1, At, B1); G_BAR;
;     }
	s_waitcnt lgkmcnt(0)
	s_waitcnt lgkmcnt(0)
	v_mfma_f32_16x16x32_bf16 v[30:33], v[196:199], v[164:167], v[30:33]
	v_mfma_f32_16x16x32_bf16 v[26:29], v[204:207], v[164:167], v[26:29]
	v_mfma_f32_16x16x32_bf16 v[22:25], v[196:199], v[172:175], v[22:25]
	v_mfma_f32_16x16x32_bf16 v[18:21], v[204:207], v[172:175], v[18:21]
	v_mfma_f32_16x16x32_bf16 v[14:17], v[196:199], v[180:183], v[14:17]
	v_mfma_f32_16x16x32_bf16 v[10:13], v[204:207], v[180:183], v[10:13]
	v_mfma_f32_16x16x32_bf16 v[6:9], v[196:199], v[188:191], v[6:9]
	v_mfma_f32_16x16x32_bf16 v[2:5], v[204:207], v[188:191], v[2:5]
	v_mfma_f32_16x16x32_bf16 v[30:33], v[200:203], v[168:171], v[30:33]
	v_mfma_f32_16x16x32_bf16 v[26:29], v[238:241], v[168:171], v[26:29]
	v_mfma_f32_16x16x32_bf16 v[22:25], v[200:203], v[176:179], v[22:25]
	v_mfma_f32_16x16x32_bf16 v[18:21], v[238:241], v[176:179], v[18:21]
	v_mfma_f32_16x16x32_bf16 v[14:17], v[200:203], v[184:187], v[14:17]
	v_mfma_f32_16x16x32_bf16 v[10:13], v[238:241], v[184:187], v[10:13]
	v_mfma_f32_16x16x32_bf16 v[6:9], v[200:203], v[192:195], v[6:9]
	v_mfma_f32_16x16x32_bf16 v[2:5], v[238:241], v[192:195], v[2:5]
	s_mov_b32 m0, s65
	v_lshl_add_u64 v[228:229], v[242:243], 0, s[16:17]
	s_barrier
	ds_read_b128 v[164:167], v211 offset:49152
	ds_read_b128 v[168:171], v211 offset:50176
	ds_read_b128 v[172:175], v211 offset:51200
	ds_read_b128 v[176:179], v211 offset:52224
	ds_read_b128 v[180:183], v211 offset:53248
	ds_read_b128 v[184:187], v211 offset:54272
	ds_read_b128 v[188:191], v211 offset:55296
	ds_read_b128 v[192:195], v211 offset:56320
	global_load_lds_dwordx4 v[228:229], off
	v_lshl_add_u64 v[228:229], v[244:245], 0, s[16:17]
	s_mov_b32 m0, s66
	s_nop 0
	global_load_lds_dwordx4 v[228:229], off
	s_barrier
	s_waitcnt lgkmcnt(0)
	s_waitcnt lgkmcnt(0)
	v_mfma_f32_16x16x32_bf16 v[66:69], v[148:151], v[164:167], v[66:69]
	v_mfma_f32_16x16x32_bf16 v[70:73], v[156:159], v[164:167], v[70:73]
	v_mfma_f32_16x16x32_bf16 v[74:77], v[148:151], v[172:175], v[74:77]
	v_mfma_f32_16x16x32_bf16 v[78:81], v[156:159], v[172:175], v[78:81]
	v_mfma_f32_16x16x32_bf16 v[82:85], v[148:151], v[180:183], v[82:85]
	v_mfma_f32_16x16x32_bf16 v[86:89], v[156:159], v[180:183], v[86:89]
	v_mfma_f32_16x16x32_bf16 v[90:93], v[148:151], v[188:191], v[90:93]
	v_mfma_f32_16x16x32_bf16 v[94:97], v[156:159], v[188:191], v[94:97]
	v_mfma_f32_16x16x32_bf16 v[66:69], v[152:155], v[168:171], v[66:69]
	v_mfma_f32_16x16x32_bf16 v[70:73], v[160:163], v[168:171], v[70:73]
	v_mfma_f32_16x16x32_bf16 v[74:77], v[152:155], v[176:179], v[74:77]
	v_mfma_f32_16x16x32_bf16 v[78:81], v[160:163], v[176:179], v[78:81]
	v_mfma_f32_16x16x32_bf16 v[82:85], v[152:155], v[184:187], v[82:85]
	v_mfma_f32_16x16x32_bf16 v[86:89], v[160:163], v[184:187], v[86:89]
	v_mfma_f32_16x16x32_bf16 v[90:93], v[152:155], v[192:195], v[90:93]
	v_mfma_f32_16x16x32_bf16 v[94:97], v[160:163], v[192:195], v[94:97]
	s_barrier
	s_mov_b32 m0, s67
	v_lshl_add_u64 v[148:149], v[246:247], 0, s[16:17]
	global_load_lds_dwordx4 v[148:149], off
	v_lshl_add_u64 v[148:149], v[248:249], 0, s[16:17]
	s_mov_b32 m0, s68
	s_nop 0
	global_load_lds_dwordx4 v[148:149], off
	s_waitcnt vmcnt(6)
	s_barrier
	v_mfma_f32_16x16x32_bf16 v[98:101], v[196:199], v[164:167], v[98:101]
	v_mfma_f32_16x16x32_bf16 v[102:105], v[204:207], v[164:167], v[102:105]
	v_mfma_f32_16x16x32_bf16 v[106:109], v[196:199], v[172:175], v[106:109]
	v_mfma_f32_16x16x32_bf16 v[110:113], v[204:207], v[172:175], v[110:113]
	v_mfma_f32_16x16x32_bf16 v[114:117], v[196:199], v[180:183], v[114:117]
	v_mfma_f32_16x16x32_bf16 v[118:121], v[204:207], v[180:183], v[118:121]
	v_mfma_f32_16x16x32_bf16 v[122:125], v[196:199], v[188:191], v[122:125]
	v_mfma_f32_16x16x32_bf16 v[126:129], v[204:207], v[188:191], v[126:129]
	v_mfma_f32_16x16x32_bf16 v[98:101], v[200:203], v[168:171], v[98:101]
	v_mfma_f32_16x16x32_bf16 v[102:105], v[238:241], v[168:171], v[102:105]
	v_mfma_f32_16x16x32_bf16 v[106:109], v[200:203], v[176:179], v[106:109]
	v_mfma_f32_16x16x32_bf16 v[110:113], v[238:241], v[176:179], v[110:113]
	v_mfma_f32_16x16x32_bf16 v[114:117], v[200:203], v[184:187], v[114:117]
	v_mfma_f32_16x16x32_bf16 v[118:121], v[238:241], v[184:187], v[118:121]
	v_mfma_f32_16x16x32_bf16 v[122:125], v[200:203], v[192:195], v[122:125]
	v_mfma_f32_16x16x32_bf16 v[126:129], v[238:241], v[192:195], v[126:129]
	s_add_i32 s50, s50, 2
	s_add_u32 s2, s2, 0x100
	s_addc_u32 s3, s3, 0
	s_cmp_gt_u32 s50, 29
	s_barrier
	s_cbranch_scc1 .LBB0_219
